# instruction selection: per-unit accumulator zeroing uses 64 v_mov_b64 instead of 128 v_mov_b32 in all ten GEMM unit loops
# speedup vs baseline: 1.0221x; 1.0021x over previous
; template <class Epi>
; __device__ __forceinline__ void gemm_phase(LAS unsigned char* lds, const Gemm g, const StaticOrder& S, const Epi& E) {
;     ...
;         const bool has_next = S.next(ui + 1, nxt);
;         const char* nA = has_next ? (const char*)g.A + (size_t)nxt.pm * tstepA : cA; const char* nB = has_next ? (const char*)g.Bt + (size_t)nxt.pn * tstepB : cB;
;         for (int t = 0; t < nt; t += 2) {
;             const bool last = (t == nt - 2);
;             const char* a2 = last ? nA : cA + (size_t)(t + 2) * kstep; const char* b2 = last ? nB : cB + (size_t)(t + 2) * kstep;
;     ...
; #pragma unroll
;         for (int a = 0; a < 2; ++a)
; #pragma unroll
;             for (int b = 0; b < 2; ++b)
; #pragma unroll
;                 for (int m = 0; m < 4; ++m)
; #pragma unroll
;                     for (int n = 0; n < 2; ++n) acc[a][b][m][n] = (f32x4){0.f, 0.f, 0.f, 0.f};
.LBB0_232:
	s_ashr_i32 s15, s14, 31
	s_lshl_b64 s[10:11], s[14:15], 19
	s_add_u32 s16, s22, s10
	s_addc_u32 s17, s23, s11
	s_and_b64 s[10:11], s[6:7], exec
	s_cselect_b32 s15, s17, s9
	s_cselect_b32 s58, s16, s8
	s_ashr_i32 s13, s12, 31
	s_lshl_b64 s[10:11], s[12:13], 19
	s_add_u32 s42, s89, s10
	s_addc_u32 s43, s95, s11
	s_and_b64 s[10:11], s[6:7], exec
	s_cselect_b32 s13, s43, s5
	s_cselect_b32 s59, s42, s4
	s_add_u32 s60, s8, 0x100
	v_mov_b32_e32 v0, 0
	s_addc_u32 s61, s9, 0
	s_mov_b32 s62, -2
	v_mov_b32_e32 v1, v0
	v_mov_b64_e32 v[2:3], 0
	v_mov_b64_e32 v[4:5], 0
	v_mov_b64_e32 v[6:7], 0
	v_mov_b64_e32 v[16:17], 0
	v_mov_b64_e32 v[18:19], 0
	v_mov_b64_e32 v[20:21], 0
	v_mov_b64_e32 v[22:23], 0
	v_mov_b64_e32 v[32:33], 0
	v_mov_b64_e32 v[34:35], 0
	v_mov_b64_e32 v[36:37], 0
	v_mov_b64_e32 v[38:39], 0
	v_mov_b64_e32 v[48:49], 0
	v_mov_b64_e32 v[50:51], 0
	v_mov_b64_e32 v[52:53], 0
	v_mov_b64_e32 v[54:55], 0
	v_mov_b64_e32 v[8:9], 0
	v_mov_b64_e32 v[10:11], 0
	v_mov_b64_e32 v[12:13], 0
	v_mov_b64_e32 v[14:15], 0
	v_mov_b64_e32 v[24:25], 0
	v_mov_b64_e32 v[26:27], 0
	v_mov_b64_e32 v[28:29], 0
	v_mov_b64_e32 v[30:31], 0
	v_mov_b64_e32 v[40:41], 0
	v_mov_b64_e32 v[42:43], 0
	v_mov_b64_e32 v[44:45], 0
	v_mov_b64_e32 v[46:47], 0
	v_mov_b64_e32 v[56:57], 0
	v_mov_b64_e32 v[58:59], 0
	v_mov_b64_e32 v[60:61], 0
	v_mov_b64_e32 v[62:63], 0
	v_mov_b64_e32 v[64:65], 0
	v_mov_b64_e32 v[66:67], 0
	v_mov_b64_e32 v[68:69], 0
	v_mov_b64_e32 v[70:71], 0
	v_mov_b64_e32 v[80:81], 0
	v_mov_b64_e32 v[82:83], 0
	v_mov_b64_e32 v[84:85], 0
	v_mov_b64_e32 v[86:87], 0
	v_mov_b64_e32 v[96:97], 0
	v_mov_b64_e32 v[98:99], 0
	v_mov_b64_e32 v[100:101], 0
	v_mov_b64_e32 v[102:103], 0
	v_mov_b64_e32 v[112:113], 0
	v_mov_b64_e32 v[114:115], 0
	v_mov_b64_e32 v[116:117], 0
	v_mov_b64_e32 v[118:119], 0
	v_mov_b64_e32 v[72:73], 0
	v_mov_b64_e32 v[74:75], 0
	v_mov_b64_e32 v[76:77], 0
	v_mov_b64_e32 v[78:79], 0
	v_mov_b64_e32 v[88:89], 0
	v_mov_b64_e32 v[90:91], 0
	v_mov_b64_e32 v[92:93], 0
	v_mov_b64_e32 v[94:95], 0
	v_mov_b64_e32 v[104:105], 0
	v_mov_b64_e32 v[106:107], 0
	v_mov_b64_e32 v[108:109], 0
	v_mov_b64_e32 v[110:111], 0
	v_mov_b64_e32 v[120:121], 0
	v_mov_b64_e32 v[122:123], 0
	v_mov_b64_e32 v[124:125], 0
	v_mov_b64_e32 v[126:127], 0

; template <class Epi>
; __device__ __forceinline__ void gemm_phase(LAS unsigned char* lds, const Gemm g, const StaticOrder& S, const Epi& E) {
;     ...
;         const bool has_next = S.next(ui + 1, nxt);
;         const char* nA = has_next ? (const char*)g.A + (size_t)nxt.pm * tstepA : cA; const char* nB = has_next ? (const char*)g.Bt + (size_t)nxt.pn * tstepB : cB;
;         for (int t = 0; t < nt; t += 2) {
;             const bool last = (t == nt - 2);
;             const char* a2 = last ? nA : cA + (size_t)(t + 2) * kstep; const char* b2 = last ? nB : cB + (size_t)(t + 2) * kstep;
;     ...
; #pragma unroll
;         for (int a = 0; a < 2; ++a)
; #pragma unroll
;             for (int b = 0; b < 2; ++b)
; #pragma unroll
;                 for (int m = 0; m < 4; ++m)
; #pragma unroll
;                     for (int n = 0; n < 2; ++n) acc[a][b][m][n] = (f32x4){0.f, 0.f, 0.f, 0.f};
.LBB0_485:
	s_ashr_i32 s17, s16, 31
	s_lshl_b64 s[38:39], s[16:17], 18
	v_readlane_b32 s6, v252, 40
	v_readlane_b32 s7, v252, 41
	s_add_u32 s38, s6, s38
	s_addc_u32 s39, s7, s39
	s_ashr_i32 s15, s14, 31
	s_lshl_b64 s[42:43], s[14:15], 18
	s_add_u32 s42, s29, s42
	v_mov_b32_e32 v123, 0
	s_addc_u32 s43, s37, s43
	s_andn2_b64 vcc, exec, s[10:11]
	v_mov_b32_e32 v122, v123
	v_mov_b32_e32 v121, v123
	v_mov_b32_e32 v120, v123
	v_mov_b32_e32 v127, v123
	v_mov_b32_e32 v126, v123
	v_mov_b32_e32 v125, v123
	v_mov_b32_e32 v124, v123
	v_mov_b32_e32 v111, v123
	v_mov_b32_e32 v110, v123
	v_mov_b32_e32 v109, v123
	v_mov_b32_e32 v108, v123
	v_mov_b32_e32 v107, v123
	v_mov_b32_e32 v106, v123
	v_mov_b32_e32 v105, v123
	v_mov_b32_e32 v104, v123
	v_mov_b32_e32 v95, v123
	v_mov_b32_e32 v94, v123
	v_mov_b32_e32 v93, v123
	v_mov_b32_e32 v92, v123
	v_mov_b32_e32 v91, v123
	v_mov_b32_e32 v90, v123
	v_mov_b32_e32 v89, v123
	v_mov_b32_e32 v88, v123
	v_mov_b32_e32 v79, v123
	v_mov_b32_e32 v78, v123
	v_mov_b32_e32 v77, v123
	v_mov_b32_e32 v76, v123
	v_mov_b32_e32 v75, v123
	v_mov_b32_e32 v74, v123
	v_mov_b32_e32 v73, v123
	v_mov_b32_e32 v72, v123
	v_mov_b32_e32 v119, v123
	v_mov_b32_e32 v118, v123
	v_mov_b32_e32 v117, v123
	v_mov_b32_e32 v116, v123
	v_mov_b32_e32 v115, v123
	v_mov_b32_e32 v114, v123
	v_mov_b32_e32 v113, v123
	v_mov_b32_e32 v112, v123
	v_mov_b32_e32 v103, v123
	v_mov_b32_e32 v102, v123
	v_mov_b32_e32 v101, v123
	v_mov_b32_e32 v100, v123
	v_mov_b32_e32 v99, v123
	v_mov_b32_e32 v98, v123
	v_mov_b32_e32 v97, v123
	v_mov_b32_e32 v96, v123
	v_mov_b32_e32 v87, v123
	v_mov_b32_e32 v86, v123
	v_mov_b32_e32 v85, v123
	v_mov_b32_e32 v84, v123
	v_mov_b32_e32 v83, v123
	v_mov_b32_e32 v82, v123
	v_mov_b32_e32 v81, v123
	v_mov_b32_e32 v80, v123
	v_mov_b32_e32 v71, v123
	v_mov_b32_e32 v70, v123
	v_mov_b32_e32 v69, v123
	v_mov_b32_e32 v68, v123
	v_mov_b32_e32 v67, v123
	v_mov_b32_e32 v66, v123
	v_mov_b32_e32 v65, v123
	v_mov_b32_e32 v64, v123
	v_mov_b32_e32 v63, v123
	v_mov_b32_e32 v62, v123
	v_mov_b32_e32 v61, v123
	v_mov_b32_e32 v60, v123
	v_mov_b32_e32 v59, v123
	v_mov_b32_e32 v58, v123
	v_mov_b32_e32 v57, v123
	v_mov_b32_e32 v56, v123
	v_mov_b32_e32 v47, v123
	v_mov_b32_e32 v46, v123
	v_mov_b32_e32 v45, v123
	v_mov_b32_e32 v44, v123
	v_mov_b32_e32 v43, v123
	v_mov_b32_e32 v42, v123
	v_mov_b32_e32 v41, v123
	v_mov_b32_e32 v40, v123
	v_mov_b32_e32 v31, v123
	v_mov_b32_e32 v30, v123
	v_mov_b32_e32 v29, v123
	v_mov_b32_e32 v28, v123
	v_mov_b32_e32 v27, v123
	v_mov_b32_e32 v26, v123
	v_mov_b32_e32 v25, v123
	v_mov_b32_e32 v24, v123
	v_mov_b32_e32 v15, v123
	v_mov_b32_e32 v14, v123
	v_mov_b32_e32 v13, v123
	v_mov_b32_e32 v12, v123
	v_mov_b32_e32 v11, v123
	v_mov_b32_e32 v10, v123
	v_mov_b32_e32 v9, v123
	v_mov_b32_e32 v8, v123
	v_mov_b32_e32 v55, v123
	v_mov_b32_e32 v54, v123
	v_mov_b32_e32 v53, v123
	v_mov_b32_e32 v52, v123
	v_mov_b32_e32 v51, v123
	v_mov_b32_e32 v50, v123
	v_mov_b32_e32 v49, v123
	v_mov_b32_e32 v48, v123
	v_mov_b32_e32 v39, v123
	v_mov_b32_e32 v38, v123
	v_mov_b32_e32 v37, v123
	v_mov_b32_e32 v36, v123
	v_mov_b32_e32 v35, v123
	v_mov_b32_e32 v34, v123
	v_mov_b32_e32 v33, v123
	v_mov_b32_e32 v32, v123
	v_mov_b32_e32 v23, v123
	v_mov_b32_e32 v22, v123
	v_mov_b32_e32 v21, v123
	v_mov_b32_e32 v20, v123
	v_mov_b32_e32 v19, v123
	v_mov_b32_e32 v18, v123
	v_mov_b32_e32 v17, v123
	v_mov_b32_e32 v16, v123
	v_mov_b32_e32 v7, v123
	v_mov_b32_e32 v6, v123
	v_mov_b32_e32 v5, v123
	v_mov_b32_e32 v4, v123
	v_mov_b32_e32 v3, v123
	v_mov_b32_e32 v2, v123
	v_mov_b32_e32 v1, v123
	v_mov_b32_e32 v0, v123
	s_cbranch_vccnz .LBB0_489
	s_and_b64 s[68:69], s[8:9], exec
	s_cselect_b32 s15, s39, s83
	s_cselect_b32 s17, s38, s82
	s_cselect_b32 s86, s43, s81
	s_cselect_b32 s87, s42, s80
	s_add_u32 s88, s80, 0x80
	s_addc_u32 s89, s81, 0
	s_add_u32 s95, s82, 0x100
	v_mov_b32_e32 v0, 0
	s_addc_u32 s96, s83, 0
	s_mov_b32 s68, 0
	v_mov_b32_e32 v1, v0
	v_mov_b64_e32 v[2:3], 0
	v_mov_b64_e32 v[4:5], 0
	v_mov_b64_e32 v[6:7], 0
	v_mov_b64_e32 v[16:17], 0
	v_mov_b64_e32 v[18:19], 0
	v_mov_b64_e32 v[20:21], 0
	v_mov_b64_e32 v[22:23], 0
	v_mov_b64_e32 v[32:33], 0
	v_mov_b64_e32 v[34:35], 0
	v_mov_b64_e32 v[36:37], 0
	v_mov_b64_e32 v[38:39], 0
	v_mov_b64_e32 v[48:49], 0
	v_mov_b64_e32 v[50:51], 0
	v_mov_b64_e32 v[52:53], 0
	v_mov_b64_e32 v[54:55], 0
	v_mov_b64_e32 v[8:9], 0
	v_mov_b64_e32 v[10:11], 0
	v_mov_b64_e32 v[12:13], 0
	v_mov_b64_e32 v[14:15], 0
	v_mov_b64_e32 v[24:25], 0
	v_mov_b64_e32 v[26:27], 0
	v_mov_b64_e32 v[28:29], 0
	v_mov_b64_e32 v[30:31], 0
	v_mov_b64_e32 v[40:41], 0
	v_mov_b64_e32 v[42:43], 0
	v_mov_b64_e32 v[44:45], 0
	v_mov_b64_e32 v[46:47], 0
	v_mov_b64_e32 v[56:57], 0
	v_mov_b64_e32 v[58:59], 0
	v_mov_b64_e32 v[60:61], 0
	v_mov_b64_e32 v[62:63], 0
	v_mov_b64_e32 v[64:65], 0
	v_mov_b64_e32 v[66:67], 0
	v_mov_b64_e32 v[68:69], 0
	v_mov_b64_e32 v[70:71], 0
	v_mov_b64_e32 v[80:81], 0
	v_mov_b64_e32 v[82:83], 0
	v_mov_b64_e32 v[84:85], 0
	v_mov_b64_e32 v[86:87], 0
	v_mov_b64_e32 v[96:97], 0
	v_mov_b64_e32 v[98:99], 0
	v_mov_b64_e32 v[100:101], 0
	v_mov_b64_e32 v[102:103], 0
	v_mov_b64_e32 v[112:113], 0
	v_mov_b64_e32 v[114:115], 0
	v_mov_b64_e32 v[116:117], 0
	v_mov_b64_e32 v[118:119], 0
	v_mov_b64_e32 v[72:73], 0
	v_mov_b64_e32 v[74:75], 0
	v_mov_b64_e32 v[76:77], 0
	v_mov_b64_e32 v[78:79], 0
	v_mov_b64_e32 v[88:89], 0
	v_mov_b64_e32 v[90:91], 0
	v_mov_b64_e32 v[92:93], 0
	v_mov_b64_e32 v[94:95], 0
	v_mov_b64_e32 v[104:105], 0
	v_mov_b64_e32 v[106:107], 0
	v_mov_b64_e32 v[108:109], 0
	v_mov_b64_e32 v[110:111], 0
	v_mov_b64_e32 v[124:125], 0
	v_mov_b64_e32 v[126:127], 0
	v_mov_b64_e32 v[120:121], 0
	v_mov_b64_e32 v[122:123], 0

; template <class Epi>
; __device__ __forceinline__ void gemm_phase(LAS unsigned char* lds, const Gemm g, const StaticOrder& S, const Epi& E) {
;     ...
;         const bool has_next = S.next(ui + 1, nxt);
;         const char* nA = has_next ? (const char*)g.A + (size_t)nxt.pm * tstepA : cA; const char* nB = has_next ? (const char*)g.Bt + (size_t)nxt.pn * tstepB : cB;
;         for (int t = 0; t < nt; t += 2) {
;             const bool last = (t == nt - 2);
;             const char* a2 = last ? nA : cA + (size_t)(t + 2) * kstep; const char* b2 = last ? nB : cB + (size_t)(t + 2) * kstep;
;     ...
; #pragma unroll
;         for (int a = 0; a < 2; ++a)
; #pragma unroll
;             for (int b = 0; b < 2; ++b)
; #pragma unroll
;                 for (int m = 0; m < 4; ++m)
; #pragma unroll
;                     for (int n = 0; n < 2; ++n) acc[a][b][m][n] = (f32x4){0.f, 0.f, 0.f, 0.f};
.LBB0_507:
	s_ashr_i32 s15, s14, 31
	s_lshl_b64 s[16:17], s[14:15], 18
	s_add_u32 s16, s29, s16
	s_addc_u32 s17, s47, s17
	s_ashr_i32 s13, s12, 31
	s_lshl_b64 s[42:43], s[12:13], 18
	v_readlane_b32 s58, v252, 34
	v_readlane_b32 s59, v252, 35
	s_add_u32 s42, s58, s42
	v_mov_b32_e32 v123, 0
	s_addc_u32 s43, s59, s43
	s_andn2_b64 vcc, exec, s[8:9]
	v_mov_b32_e32 v122, v123
	v_mov_b32_e32 v121, v123
	v_mov_b32_e32 v120, v123
	v_mov_b32_e32 v127, v123
	v_mov_b32_e32 v126, v123
	v_mov_b32_e32 v125, v123
	v_mov_b32_e32 v124, v123
	v_mov_b32_e32 v111, v123
	v_mov_b32_e32 v110, v123
	v_mov_b32_e32 v109, v123
	v_mov_b32_e32 v108, v123
	v_mov_b32_e32 v107, v123
	v_mov_b32_e32 v106, v123
	v_mov_b32_e32 v105, v123
	v_mov_b32_e32 v104, v123
	v_mov_b32_e32 v95, v123
	v_mov_b32_e32 v94, v123
	v_mov_b32_e32 v93, v123
	v_mov_b32_e32 v92, v123
	v_mov_b32_e32 v91, v123
	v_mov_b32_e32 v90, v123
	v_mov_b32_e32 v89, v123
	v_mov_b32_e32 v88, v123
	v_mov_b32_e32 v79, v123
	v_mov_b32_e32 v78, v123
	v_mov_b32_e32 v77, v123
	v_mov_b32_e32 v76, v123
	v_mov_b32_e32 v75, v123
	v_mov_b32_e32 v74, v123
	v_mov_b32_e32 v73, v123
	v_mov_b32_e32 v72, v123
	v_mov_b32_e32 v119, v123
	v_mov_b32_e32 v118, v123
	v_mov_b32_e32 v117, v123
	v_mov_b32_e32 v116, v123
	v_mov_b32_e32 v115, v123
	v_mov_b32_e32 v114, v123
	v_mov_b32_e32 v113, v123
	v_mov_b32_e32 v112, v123
	v_mov_b32_e32 v103, v123
	v_mov_b32_e32 v102, v123
	v_mov_b32_e32 v101, v123
	v_mov_b32_e32 v100, v123
	v_mov_b32_e32 v99, v123
	v_mov_b32_e32 v98, v123
	v_mov_b32_e32 v97, v123
	v_mov_b32_e32 v96, v123
	v_mov_b32_e32 v87, v123
	v_mov_b32_e32 v86, v123
	v_mov_b32_e32 v85, v123
	v_mov_b32_e32 v84, v123
	v_mov_b32_e32 v83, v123
	v_mov_b32_e32 v82, v123
	v_mov_b32_e32 v81, v123
	v_mov_b32_e32 v80, v123
	v_mov_b32_e32 v71, v123
	v_mov_b32_e32 v70, v123
	v_mov_b32_e32 v69, v123
	v_mov_b32_e32 v68, v123
	v_mov_b32_e32 v67, v123
	v_mov_b32_e32 v66, v123
	v_mov_b32_e32 v65, v123
	v_mov_b32_e32 v64, v123
	v_mov_b32_e32 v63, v123
	v_mov_b32_e32 v62, v123
	v_mov_b32_e32 v61, v123
	v_mov_b32_e32 v60, v123
	v_mov_b32_e32 v59, v123
	v_mov_b32_e32 v58, v123
	v_mov_b32_e32 v57, v123
	v_mov_b32_e32 v56, v123
	v_mov_b32_e32 v47, v123
	v_mov_b32_e32 v46, v123
	v_mov_b32_e32 v45, v123
	v_mov_b32_e32 v44, v123
	v_mov_b32_e32 v43, v123
	v_mov_b32_e32 v42, v123
	v_mov_b32_e32 v41, v123
	v_mov_b32_e32 v40, v123
	v_mov_b32_e32 v31, v123
	v_mov_b32_e32 v30, v123
	v_mov_b32_e32 v29, v123
	v_mov_b32_e32 v28, v123
	v_mov_b32_e32 v27, v123
	v_mov_b32_e32 v26, v123
	v_mov_b32_e32 v25, v123
	v_mov_b32_e32 v24, v123
	v_mov_b32_e32 v15, v123
	v_mov_b32_e32 v14, v123
	v_mov_b32_e32 v13, v123
	v_mov_b32_e32 v12, v123
	v_mov_b32_e32 v11, v123
	v_mov_b32_e32 v10, v123
	v_mov_b32_e32 v9, v123
	v_mov_b32_e32 v8, v123
	v_mov_b32_e32 v55, v123
	v_mov_b32_e32 v54, v123
	v_mov_b32_e32 v53, v123
	v_mov_b32_e32 v52, v123
	v_mov_b32_e32 v51, v123
	v_mov_b32_e32 v50, v123
	v_mov_b32_e32 v49, v123
	v_mov_b32_e32 v48, v123
	v_mov_b32_e32 v39, v123
	v_mov_b32_e32 v38, v123
	v_mov_b32_e32 v37, v123
	v_mov_b32_e32 v36, v123
	v_mov_b32_e32 v35, v123
	v_mov_b32_e32 v34, v123
	v_mov_b32_e32 v33, v123
	v_mov_b32_e32 v32, v123
	v_mov_b32_e32 v23, v123
	v_mov_b32_e32 v22, v123
	v_mov_b32_e32 v21, v123
	v_mov_b32_e32 v20, v123
	v_mov_b32_e32 v19, v123
	v_mov_b32_e32 v18, v123
	v_mov_b32_e32 v17, v123
	v_mov_b32_e32 v16, v123
	v_mov_b32_e32 v7, v123
	v_mov_b32_e32 v6, v123
	v_mov_b32_e32 v5, v123
	v_mov_b32_e32 v4, v123
	v_mov_b32_e32 v3, v123
	v_mov_b32_e32 v2, v123
	v_mov_b32_e32 v1, v123
	v_mov_b32_e32 v0, v123
	s_cbranch_vccnz .LBB0_511
	s_and_b64 s[58:59], s[6:7], exec
	s_cselect_b32 s13, s17, s5
	s_cselect_b32 s15, s16, s4
	s_cselect_b32 s57, s43, s39
	s_cselect_b32 s58, s42, s38
	s_add_u32 s59, s38, 0x80
	s_addc_u32 s60, s39, 0
	s_add_u32 s61, s4, 0x100
	v_mov_b32_e32 v0, 0
	s_addc_u32 s62, s5, 0
	s_mov_b32 s4, 0
	v_mov_b32_e32 v1, v0
	v_mov_b64_e32 v[2:3], 0
	v_mov_b64_e32 v[4:5], 0
	v_mov_b64_e32 v[6:7], 0
	v_mov_b64_e32 v[16:17], 0
	v_mov_b64_e32 v[18:19], 0
	v_mov_b64_e32 v[20:21], 0
	v_mov_b64_e32 v[22:23], 0
	v_mov_b64_e32 v[32:33], 0
	v_mov_b64_e32 v[34:35], 0
	v_mov_b64_e32 v[36:37], 0
	v_mov_b64_e32 v[38:39], 0
	v_mov_b64_e32 v[48:49], 0
	v_mov_b64_e32 v[50:51], 0
	v_mov_b64_e32 v[52:53], 0
	v_mov_b64_e32 v[54:55], 0
	v_mov_b64_e32 v[8:9], 0
	v_mov_b64_e32 v[10:11], 0
	v_mov_b64_e32 v[12:13], 0
	v_mov_b64_e32 v[14:15], 0
	v_mov_b64_e32 v[24:25], 0
	v_mov_b64_e32 v[26:27], 0
	v_mov_b64_e32 v[28:29], 0
	v_mov_b64_e32 v[30:31], 0
	v_mov_b64_e32 v[40:41], 0
	v_mov_b64_e32 v[42:43], 0
	v_mov_b64_e32 v[44:45], 0
	v_mov_b64_e32 v[46:47], 0
	v_mov_b64_e32 v[56:57], 0
	v_mov_b64_e32 v[58:59], 0
	v_mov_b64_e32 v[60:61], 0
	v_mov_b64_e32 v[62:63], 0
	v_mov_b64_e32 v[64:65], 0
	v_mov_b64_e32 v[66:67], 0
	v_mov_b64_e32 v[68:69], 0
	v_mov_b64_e32 v[70:71], 0
	v_mov_b64_e32 v[80:81], 0
	v_mov_b64_e32 v[82:83], 0
	v_mov_b64_e32 v[84:85], 0
	v_mov_b64_e32 v[86:87], 0
	v_mov_b64_e32 v[96:97], 0
	v_mov_b64_e32 v[98:99], 0
	v_mov_b64_e32 v[100:101], 0
	v_mov_b64_e32 v[102:103], 0
	v_mov_b64_e32 v[112:113], 0
	v_mov_b64_e32 v[114:115], 0
	v_mov_b64_e32 v[116:117], 0
	v_mov_b64_e32 v[118:119], 0
	v_mov_b64_e32 v[72:73], 0
	v_mov_b64_e32 v[74:75], 0
	v_mov_b64_e32 v[76:77], 0
	v_mov_b64_e32 v[78:79], 0
	v_mov_b64_e32 v[88:89], 0
	v_mov_b64_e32 v[90:91], 0
	v_mov_b64_e32 v[92:93], 0
	v_mov_b64_e32 v[94:95], 0
	v_mov_b64_e32 v[104:105], 0
	v_mov_b64_e32 v[106:107], 0
	v_mov_b64_e32 v[108:109], 0
	v_mov_b64_e32 v[110:111], 0
	v_mov_b64_e32 v[124:125], 0
	v_mov_b64_e32 v[126:127], 0
	v_mov_b64_e32 v[120:121], 0
	v_mov_b64_e32 v[122:123], 0

; template <class Epi>
; __device__ __forceinline__ void gemm_phase(LAS unsigned char* lds, const Gemm g, const StaticOrder& S, const Epi& E) {
;     ...
;         const bool has_next = S.next(ui + 1, nxt);
;         const char* nA = has_next ? (const char*)g.A + (size_t)nxt.pm * tstepA : cA; const char* nB = has_next ? (const char*)g.Bt + (size_t)nxt.pn * tstepB : cB;
;         for (int t = 0; t < nt; t += 2) {
;             const bool last = (t == nt - 2);
;             const char* a2 = last ? nA : cA + (size_t)(t + 2) * kstep; const char* b2 = last ? nB : cB + (size_t)(t + 2) * kstep;
;     ...
; #pragma unroll
;         for (int a = 0; a < 2; ++a)
; #pragma unroll
;             for (int b = 0; b < 2; ++b)
; #pragma unroll
;                 for (int m = 0; m < 4; ++m)
; #pragma unroll
;                     for (int n = 0; n < 2; ++n) acc[a][b][m][n] = (f32x4){0.f, 0.f, 0.f, 0.f};
.LBB0_583:
	s_ashr_i32 s43, s42, 31
	s_lshl_b64 s[68:69], s[42:43], 19
	s_add_u32 s80, s22, s68
	s_addc_u32 s81, s23, s69
	s_and_b64 s[68:69], s[6:7], exec
	s_cselect_b32 s43, s81, s11
	s_cselect_b32 s67, s80, s10
	s_ashr_i32 s39, s38, 31
	s_lshl_b64 s[68:69], s[38:39], 19
	s_add_u32 s82, s89, s68
	s_addc_u32 s83, s95, s69
	s_and_b64 s[68:69], s[6:7], exec
	s_cselect_b32 s39, s83, s9
	s_cselect_b32 s86, s82, s8
	s_add_u32 s87, s10, 0x100
	v_mov_b32_e32 v80, 0
	s_addc_u32 s88, s11, 0
	s_mov_b32 s68, -2
	v_mov_b32_e32 v81, v80
	v_mov_b64_e32 v[82:83], 0
	v_mov_b64_e32 v[0:1], 0
	v_mov_b64_e32 v[2:3], 0
	v_mov_b64_e32 v[92:93], 0
	v_mov_b64_e32 v[94:95], 0
	v_mov_b64_e32 v[4:5], 0
	v_mov_b64_e32 v[6:7], 0
	v_mov_b64_e32 v[96:97], 0
	v_mov_b64_e32 v[98:99], 0
	v_mov_b64_e32 v[8:9], 0
	v_mov_b64_e32 v[10:11], 0
	v_mov_b64_e32 v[100:101], 0
	v_mov_b64_e32 v[102:103], 0
	v_mov_b64_e32 v[20:21], 0
	v_mov_b64_e32 v[22:23], 0
	v_mov_b64_e32 v[84:85], 0
	v_mov_b64_e32 v[86:87], 0
	v_mov_b64_e32 v[88:89], 0
	v_mov_b64_e32 v[90:91], 0
	v_mov_b64_e32 v[12:13], 0
	v_mov_b64_e32 v[14:15], 0
	v_mov_b64_e32 v[16:17], 0
	v_mov_b64_e32 v[18:19], 0
	v_mov_b64_e32 v[24:25], 0
	v_mov_b64_e32 v[26:27], 0
	v_mov_b64_e32 v[28:29], 0
	v_mov_b64_e32 v[30:31], 0
	v_mov_b64_e32 v[32:33], 0
	v_mov_b64_e32 v[34:35], 0
	v_mov_b64_e32 v[36:37], 0
	v_mov_b64_e32 v[38:39], 0
	v_mov_b64_e32 v[108:109], 0
	v_mov_b64_e32 v[110:111], 0
	v_mov_b64_e32 v[40:41], 0
	v_mov_b64_e32 v[42:43], 0
	v_mov_b64_e32 v[116:117], 0
	v_mov_b64_e32 v[118:119], 0
	v_mov_b64_e32 v[44:45], 0
	v_mov_b64_e32 v[46:47], 0
	v_mov_b64_e32 v[120:121], 0
	v_mov_b64_e32 v[122:123], 0
	v_mov_b64_e32 v[48:49], 0
	v_mov_b64_e32 v[50:51], 0
	v_mov_b64_e32 v[124:125], 0
	v_mov_b64_e32 v[126:127], 0
	v_mov_b64_e32 v[68:69], 0
	v_mov_b64_e32 v[70:71], 0
	v_mov_b64_e32 v[104:105], 0
	v_mov_b64_e32 v[106:107], 0
	v_mov_b64_e32 v[112:113], 0
	v_mov_b64_e32 v[114:115], 0
	v_mov_b64_e32 v[52:53], 0
	v_mov_b64_e32 v[54:55], 0
	v_mov_b64_e32 v[56:57], 0
	v_mov_b64_e32 v[58:59], 0
	v_mov_b64_e32 v[60:61], 0
	v_mov_b64_e32 v[62:63], 0
	v_mov_b64_e32 v[64:65], 0
	v_mov_b64_e32 v[66:67], 0
	v_mov_b64_e32 v[72:73], 0
	v_mov_b64_e32 v[74:75], 0
	v_mov_b64_e32 v[76:77], 0
	v_mov_b64_e32 v[78:79], 0

; template <class Epi>
; __device__ __forceinline__ void gemm_phase(LAS unsigned char* lds, const Gemm g, const StaticOrder& S, const Epi& E) {
;     ...
;         const bool has_next = S.next(ui + 1, nxt);
;         const char* nA = has_next ? (const char*)g.A + (size_t)nxt.pm * tstepA : cA; const char* nB = has_next ? (const char*)g.Bt + (size_t)nxt.pn * tstepB : cB;
;         for (int t = 0; t < nt; t += 2) {
;             const bool last = (t == nt - 2);
;             const char* a2 = last ? nA : cA + (size_t)(t + 2) * kstep; const char* b2 = last ? nB : cB + (size_t)(t + 2) * kstep;
;     ...
; #pragma unroll
;         for (int a = 0; a < 2; ++a)
; #pragma unroll
;             for (int b = 0; b < 2; ++b)
; #pragma unroll
;                 for (int m = 0; m < 4; ++m)
; #pragma unroll
;                     for (int n = 0; n < 2; ++n) acc[a][b][m][n] = (f32x4){0.f, 0.f, 0.f, 0.f};
.LBB0_660:
	s_lshr_b64 s[14:15], s[12:13], 3
	s_and_b64 s[16:17], s[8:9], exec
	s_cselect_b32 s37, s14, s80
	s_ashr_i64 s[16:17], s[36:37], 15
	s_add_u32 s16, s6, s16
	v_mov_b32_e32 v63, 0
	s_addc_u32 s17, s7, s17
	s_andn2_b64 vcc, exec, s[2:3]
	v_mov_b32_e32 v62, v63
	v_mov_b32_e32 v61, v63
	v_mov_b32_e32 v60, v63
	v_mov_b32_e32 v59, v63
	v_mov_b32_e32 v58, v63
	v_mov_b32_e32 v57, v63
	v_mov_b32_e32 v56, v63
	v_mov_b32_e32 v55, v63
	v_mov_b32_e32 v54, v63
	v_mov_b32_e32 v53, v63
	v_mov_b32_e32 v52, v63
	v_mov_b32_e32 v51, v63
	v_mov_b32_e32 v50, v63
	v_mov_b32_e32 v49, v63
	v_mov_b32_e32 v48, v63
	v_mov_b32_e32 v47, v63
	v_mov_b32_e32 v46, v63
	v_mov_b32_e32 v45, v63
	v_mov_b32_e32 v44, v63
	v_mov_b32_e32 v43, v63
	v_mov_b32_e32 v42, v63
	v_mov_b32_e32 v41, v63
	v_mov_b32_e32 v40, v63
	v_mov_b32_e32 v39, v63
	v_mov_b32_e32 v38, v63
	v_mov_b32_e32 v37, v63
	v_mov_b32_e32 v36, v63
	v_mov_b32_e32 v35, v63
	v_mov_b32_e32 v34, v63
	v_mov_b32_e32 v33, v63
	v_mov_b32_e32 v32, v63
	v_mov_b32_e32 v31, v63
	v_mov_b32_e32 v30, v63
	v_mov_b32_e32 v29, v63
	v_mov_b32_e32 v28, v63
	v_mov_b32_e32 v27, v63
	v_mov_b32_e32 v26, v63
	v_mov_b32_e32 v25, v63
	v_mov_b32_e32 v24, v63
	v_mov_b32_e32 v23, v63
	v_mov_b32_e32 v22, v63
	v_mov_b32_e32 v21, v63
	v_mov_b32_e32 v20, v63
	v_mov_b32_e32 v19, v63
	v_mov_b32_e32 v18, v63
	v_mov_b32_e32 v17, v63
	v_mov_b32_e32 v16, v63
	v_mov_b32_e32 v15, v63
	v_mov_b32_e32 v14, v63
	v_mov_b32_e32 v13, v63
	v_mov_b32_e32 v12, v63
	v_mov_b32_e32 v11, v63
	v_mov_b32_e32 v10, v63
	v_mov_b32_e32 v9, v63
	v_mov_b32_e32 v8, v63
	v_mov_b32_e32 v7, v63
	v_mov_b32_e32 v6, v63
	v_mov_b32_e32 v5, v63
	v_mov_b32_e32 v4, v63
	v_mov_b32_e32 v3, v63
	v_mov_b32_e32 v2, v63
	v_mov_b32_e32 v1, v63
	v_mov_b32_e32 v0, v63
	s_cbranch_vccnz .LBB0_663
	s_and_b64 s[68:69], s[8:9], exec
	s_cselect_b32 s13, s17, s39
	s_cselect_b32 s37, s16, s38
	s_add_u32 s67, s38, 0x80
	s_addc_u32 s68, s39, 0
	s_add_u32 s69, s42, 0x100
	v_mov_b32_e32 v0, 0
	s_addc_u32 s84, s43, 0
	s_mov_b32 s38, 0
	v_mov_b32_e32 v1, v0
	v_mov_b64_e32 v[2:3], 0
	v_mov_b64_e32 v[4:5], 0
	v_mov_b64_e32 v[6:7], 0
	v_mov_b64_e32 v[8:9], 0
	v_mov_b64_e32 v[10:11], 0
	v_mov_b64_e32 v[12:13], 0
	v_mov_b64_e32 v[14:15], 0
	v_mov_b64_e32 v[16:17], 0
	v_mov_b64_e32 v[18:19], 0
	v_mov_b64_e32 v[20:21], 0
	v_mov_b64_e32 v[22:23], 0
	v_mov_b64_e32 v[24:25], 0
	v_mov_b64_e32 v[26:27], 0
	v_mov_b64_e32 v[28:29], 0
	v_mov_b64_e32 v[30:31], 0
	v_mov_b64_e32 v[32:33], 0
	v_mov_b64_e32 v[34:35], 0
	v_mov_b64_e32 v[36:37], 0
	v_mov_b64_e32 v[38:39], 0
	v_mov_b64_e32 v[40:41], 0
	v_mov_b64_e32 v[42:43], 0
	v_mov_b64_e32 v[44:45], 0
	v_mov_b64_e32 v[46:47], 0
	v_mov_b64_e32 v[48:49], 0
	v_mov_b64_e32 v[50:51], 0
	v_mov_b64_e32 v[52:53], 0
	v_mov_b64_e32 v[54:55], 0
	v_mov_b64_e32 v[56:57], 0
	v_mov_b64_e32 v[58:59], 0
	v_mov_b64_e32 v[60:61], 0
	v_mov_b64_e32 v[62:63], 0

; template <class Epi>
; __device__ __forceinline__ void gemm_phase(LAS unsigned char* lds, const Gemm g, const StaticOrder& S, const Epi& E) {
;     ...
;         const bool has_next = S.next(ui + 1, nxt);
;         const char* nA = has_next ? (const char*)g.A + (size_t)nxt.pm * tstepA : cA; const char* nB = has_next ? (const char*)g.Bt + (size_t)nxt.pn * tstepB : cB;
;         for (int t = 0; t < nt; t += 2) {
;             const bool last = (t == nt - 2);
;             const char* a2 = last ? nA : cA + (size_t)(t + 2) * kstep; const char* b2 = last ? nB : cB + (size_t)(t + 2) * kstep;
;     ...
; #pragma unroll
;         for (int a = 0; a < 2; ++a)
; #pragma unroll
;             for (int b = 0; b < 2; ++b)
; #pragma unroll
;                 for (int m = 0; m < 4; ++m)
; #pragma unroll
;                     for (int n = 0; n < 2; ++n) acc[a][b][m][n] = (f32x4){0.f, 0.f, 0.f, 0.f};
.LBB0_795:
	v_mov_b32_e32 v127, 0
	s_andn2_b64 vcc, exec, s[12:13]
	v_mov_b32_e32 v126, v127
	v_mov_b32_e32 v125, v127
	v_mov_b32_e32 v124, v127
	v_mov_b32_e32 v123, v127
	v_mov_b32_e32 v122, v127
	v_mov_b32_e32 v121, v127
	v_mov_b32_e32 v120, v127
	v_mov_b32_e32 v111, v127
	v_mov_b32_e32 v110, v127
	v_mov_b32_e32 v109, v127
	v_mov_b32_e32 v108, v127
	v_mov_b32_e32 v107, v127
	v_mov_b32_e32 v106, v127
	v_mov_b32_e32 v105, v127
	v_mov_b32_e32 v104, v127
	v_mov_b32_e32 v95, v127
	v_mov_b32_e32 v94, v127
	v_mov_b32_e32 v93, v127
	v_mov_b32_e32 v92, v127
	v_mov_b32_e32 v91, v127
	v_mov_b32_e32 v90, v127
	v_mov_b32_e32 v89, v127
	v_mov_b32_e32 v88, v127
	v_mov_b32_e32 v79, v127
	v_mov_b32_e32 v78, v127
	v_mov_b32_e32 v77, v127
	v_mov_b32_e32 v76, v127
	v_mov_b32_e32 v75, v127
	v_mov_b32_e32 v74, v127
	v_mov_b32_e32 v73, v127
	v_mov_b32_e32 v72, v127
	v_mov_b32_e32 v119, v127
	v_mov_b32_e32 v118, v127
	v_mov_b32_e32 v117, v127
	v_mov_b32_e32 v116, v127
	v_mov_b32_e32 v115, v127
	v_mov_b32_e32 v114, v127
	v_mov_b32_e32 v113, v127
	v_mov_b32_e32 v112, v127
	v_mov_b32_e32 v103, v127
	v_mov_b32_e32 v102, v127
	v_mov_b32_e32 v101, v127
	v_mov_b32_e32 v100, v127
	v_mov_b32_e32 v99, v127
	v_mov_b32_e32 v98, v127
	v_mov_b32_e32 v97, v127
	v_mov_b32_e32 v96, v127
	v_mov_b32_e32 v87, v127
	v_mov_b32_e32 v86, v127
	v_mov_b32_e32 v85, v127
	v_mov_b32_e32 v84, v127
	v_mov_b32_e32 v83, v127
	v_mov_b32_e32 v82, v127
	v_mov_b32_e32 v81, v127
	v_mov_b32_e32 v80, v127
	v_mov_b32_e32 v71, v127
	v_mov_b32_e32 v70, v127
	v_mov_b32_e32 v69, v127
	v_mov_b32_e32 v68, v127
	v_mov_b32_e32 v67, v127
	v_mov_b32_e32 v66, v127
	v_mov_b32_e32 v65, v127
	v_mov_b32_e32 v64, v127
	v_mov_b32_e32 v63, v127
	v_mov_b32_e32 v62, v127
	v_mov_b32_e32 v61, v127
	v_mov_b32_e32 v60, v127
	v_mov_b32_e32 v59, v127
	v_mov_b32_e32 v58, v127
	v_mov_b32_e32 v57, v127
	v_mov_b32_e32 v56, v127
	v_mov_b32_e32 v47, v127
	v_mov_b32_e32 v46, v127
	v_mov_b32_e32 v45, v127
	v_mov_b32_e32 v44, v127
	v_mov_b32_e32 v43, v127
	v_mov_b32_e32 v42, v127
	v_mov_b32_e32 v41, v127
	v_mov_b32_e32 v40, v127
	v_mov_b32_e32 v31, v127
	v_mov_b32_e32 v30, v127
	v_mov_b32_e32 v29, v127
	v_mov_b32_e32 v28, v127
	v_mov_b32_e32 v27, v127
	v_mov_b32_e32 v26, v127
	v_mov_b32_e32 v25, v127
	v_mov_b32_e32 v24, v127
	v_mov_b32_e32 v15, v127
	v_mov_b32_e32 v14, v127
	v_mov_b32_e32 v13, v127
	v_mov_b32_e32 v12, v127
	v_mov_b32_e32 v11, v127
	v_mov_b32_e32 v10, v127
	v_mov_b32_e32 v9, v127
	v_mov_b32_e32 v8, v127
	v_mov_b32_e32 v55, v127
	v_mov_b32_e32 v54, v127
	v_mov_b32_e32 v53, v127
	v_mov_b32_e32 v52, v127
	v_mov_b32_e32 v51, v127
	v_mov_b32_e32 v50, v127
	v_mov_b32_e32 v49, v127
	v_mov_b32_e32 v48, v127
	v_mov_b32_e32 v39, v127
	v_mov_b32_e32 v38, v127
	v_mov_b32_e32 v37, v127
	v_mov_b32_e32 v36, v127
	v_mov_b32_e32 v35, v127
	v_mov_b32_e32 v34, v127
	v_mov_b32_e32 v33, v127
	v_mov_b32_e32 v32, v127
	v_mov_b32_e32 v23, v127
	v_mov_b32_e32 v22, v127
	v_mov_b32_e32 v21, v127
	v_mov_b32_e32 v20, v127
	v_mov_b32_e32 v19, v127
	v_mov_b32_e32 v18, v127
	v_mov_b32_e32 v17, v127
	v_mov_b32_e32 v16, v127
	v_mov_b32_e32 v7, v127
	v_mov_b32_e32 v6, v127
	v_mov_b32_e32 v5, v127
	v_mov_b32_e32 v4, v127
	v_mov_b32_e32 v3, v127
	v_mov_b32_e32 v2, v127
	v_mov_b32_e32 v1, v127
	v_mov_b32_e32 v0, v127
	s_cbranch_vccnz .LBB0_799
	s_add_u32 s1, s4, 0x80
	s_addc_u32 s43, s5, 0
	s_add_u32 s50, s38, 0x100
	v_mov_b32_e32 v0, 0
	v_mov_b32_e32 v141, 0x4f
	s_addc_u32 s51, s39, 0
	s_mov_b32 s4, 0
	v_mov_b32_e32 v1, v0
	v_mov_b64_e32 v[2:3], 0
	v_mov_b64_e32 v[4:5], 0
	v_mov_b64_e32 v[6:7], 0
	v_mov_b64_e32 v[16:17], 0
	v_mov_b64_e32 v[18:19], 0
	v_mov_b64_e32 v[20:21], 0
	v_mov_b64_e32 v[22:23], 0
	v_mov_b64_e32 v[32:33], 0
	v_mov_b64_e32 v[34:35], 0
	v_mov_b64_e32 v[36:37], 0
	v_mov_b64_e32 v[38:39], 0
	v_mov_b64_e32 v[48:49], 0
	v_mov_b64_e32 v[50:51], 0
	v_mov_b64_e32 v[52:53], 0
	v_mov_b64_e32 v[54:55], 0
	v_mov_b64_e32 v[8:9], 0
	v_mov_b64_e32 v[10:11], 0
	v_mov_b64_e32 v[12:13], 0
	v_mov_b64_e32 v[14:15], 0
	v_mov_b64_e32 v[24:25], 0
	v_mov_b64_e32 v[26:27], 0
	v_mov_b64_e32 v[28:29], 0
	v_mov_b64_e32 v[30:31], 0
	v_mov_b64_e32 v[40:41], 0
	v_mov_b64_e32 v[42:43], 0
	v_mov_b64_e32 v[44:45], 0
	v_mov_b64_e32 v[46:47], 0
	v_mov_b64_e32 v[56:57], 0
	v_mov_b64_e32 v[58:59], 0
	v_mov_b64_e32 v[60:61], 0
	v_mov_b64_e32 v[62:63], 0
	v_mov_b64_e32 v[64:65], 0
	v_mov_b64_e32 v[66:67], 0
	v_mov_b64_e32 v[68:69], 0
	v_mov_b64_e32 v[70:71], 0
	v_mov_b64_e32 v[80:81], 0
	v_mov_b64_e32 v[82:83], 0
	v_mov_b64_e32 v[84:85], 0
	v_mov_b64_e32 v[86:87], 0
	v_mov_b64_e32 v[96:97], 0
	v_mov_b64_e32 v[98:99], 0
	v_mov_b64_e32 v[100:101], 0
	v_mov_b64_e32 v[102:103], 0
	v_mov_b64_e32 v[112:113], 0
	v_mov_b64_e32 v[114:115], 0
	v_mov_b64_e32 v[116:117], 0
	v_mov_b64_e32 v[118:119], 0
	v_mov_b64_e32 v[72:73], 0
	v_mov_b64_e32 v[74:75], 0
	v_mov_b64_e32 v[76:77], 0
	v_mov_b64_e32 v[78:79], 0
	v_mov_b64_e32 v[88:89], 0
	v_mov_b64_e32 v[90:91], 0
	v_mov_b64_e32 v[92:93], 0
	v_mov_b64_e32 v[94:95], 0
	v_mov_b64_e32 v[104:105], 0
	v_mov_b64_e32 v[106:107], 0
	v_mov_b64_e32 v[108:109], 0
	v_mov_b64_e32 v[110:111], 0
	v_mov_b64_e32 v[120:121], 0
	v_mov_b64_e32 v[122:123], 0
	v_mov_b64_e32 v[124:125], 0
	v_mov_b64_e32 v[126:127], 0

; template <class Epi>
; __device__ __forceinline__ void gemm_phase(LAS unsigned char* lds, const Gemm g, const StaticOrder& S, const Epi& E) {
;     ...
;         const bool has_next = S.next(ui + 1, nxt);
;         const char* nA = has_next ? (const char*)g.A + (size_t)nxt.pm * tstepA : cA; const char* nB = has_next ? (const char*)g.Bt + (size_t)nxt.pn * tstepB : cB;
;         for (int t = 0; t < nt; t += 2) {
;             const bool last = (t == nt - 2);
;             const char* a2 = last ? nA : cA + (size_t)(t + 2) * kstep; const char* b2 = last ? nB : cB + (size_t)(t + 2) * kstep;
;     ...
; #pragma unroll
;         for (int a = 0; a < 2; ++a)
; #pragma unroll
;             for (int b = 0; b < 2; ++b)
; #pragma unroll
;                 for (int m = 0; m < 4; ++m)
; #pragma unroll
;                     for (int n = 0; n < 2; ++n) acc[a][b][m][n] = (f32x4){0.f, 0.f, 0.f, 0.f};
.LBB0_869:
	s_ashr_i32 s11, s10, 31
	s_lshl_b64 s[12:13], s[10:11], 18
	s_add_u32 s12, s30, s12
	s_addc_u32 s13, s31, s13
	s_and_b64 s[14:15], s[6:7], exec
	s_cselect_b32 s11, s13, s39
	s_cselect_b32 s65, s12, s38
	s_ashr_i32 s9, s8, 31
	s_lshl_b64 s[14:15], s[8:9], 18
	s_add_u32 s14, s28, s14
	s_addc_u32 s15, s29, s15
	s_and_b64 s[42:43], s[6:7], exec
	s_cselect_b32 s9, s15, s17
	s_cselect_b32 s66, s14, s16
	s_add_u32 s67, s38, 0x100
	v_mov_b32_e32 v0, 0
	s_addc_u32 s84, s39, 0
	s_mov_b32 s68, -2
	v_mov_b32_e32 v1, v0
	v_mov_b64_e32 v[2:3], 0
	v_mov_b64_e32 v[4:5], 0
	v_mov_b64_e32 v[6:7], 0
	v_mov_b64_e32 v[16:17], 0
	v_mov_b64_e32 v[18:19], 0
	v_mov_b64_e32 v[20:21], 0
	v_mov_b64_e32 v[22:23], 0
	v_mov_b64_e32 v[32:33], 0
	v_mov_b64_e32 v[34:35], 0
	v_mov_b64_e32 v[36:37], 0
	v_mov_b64_e32 v[38:39], 0
	v_mov_b64_e32 v[48:49], 0
	v_mov_b64_e32 v[50:51], 0
	v_mov_b64_e32 v[52:53], 0
	v_mov_b64_e32 v[54:55], 0
	v_mov_b64_e32 v[8:9], 0
	v_mov_b64_e32 v[10:11], 0
	v_mov_b64_e32 v[12:13], 0
	v_mov_b64_e32 v[14:15], 0
	v_mov_b64_e32 v[24:25], 0
	v_mov_b64_e32 v[26:27], 0
	v_mov_b64_e32 v[28:29], 0
	v_mov_b64_e32 v[30:31], 0
	v_mov_b64_e32 v[40:41], 0
	v_mov_b64_e32 v[42:43], 0
	v_mov_b64_e32 v[44:45], 0
	v_mov_b64_e32 v[46:47], 0
	v_mov_b64_e32 v[56:57], 0
	v_mov_b64_e32 v[58:59], 0
	v_mov_b64_e32 v[60:61], 0
	v_mov_b64_e32 v[62:63], 0
	v_mov_b64_e32 v[64:65], 0
	v_mov_b64_e32 v[66:67], 0
	v_mov_b64_e32 v[68:69], 0
	v_mov_b64_e32 v[70:71], 0
	v_mov_b64_e32 v[80:81], 0
	v_mov_b64_e32 v[82:83], 0
	v_mov_b64_e32 v[84:85], 0
	v_mov_b64_e32 v[86:87], 0
	v_mov_b64_e32 v[96:97], 0
	v_mov_b64_e32 v[98:99], 0
	v_mov_b64_e32 v[100:101], 0
	v_mov_b64_e32 v[102:103], 0
	v_mov_b64_e32 v[112:113], 0
	v_mov_b64_e32 v[114:115], 0
	v_mov_b64_e32 v[116:117], 0
	v_mov_b64_e32 v[118:119], 0
	v_mov_b64_e32 v[72:73], 0
	v_mov_b64_e32 v[74:75], 0
	v_mov_b64_e32 v[76:77], 0
	v_mov_b64_e32 v[78:79], 0
	v_mov_b64_e32 v[88:89], 0
	v_mov_b64_e32 v[90:91], 0
	v_mov_b64_e32 v[92:93], 0
	v_mov_b64_e32 v[94:95], 0
	v_mov_b64_e32 v[104:105], 0
	v_mov_b64_e32 v[106:107], 0
	v_mov_b64_e32 v[108:109], 0
	v_mov_b64_e32 v[110:111], 0
	v_mov_b64_e32 v[120:121], 0
	v_mov_b64_e32 v[122:123], 0
	v_mov_b64_e32 v[124:125], 0
	v_mov_b64_e32 v[126:127], 0

; template <class Epi>
; __device__ __forceinline__ void gemm_phase(LAS unsigned char* lds, const Gemm g, const StaticOrder& S, const Epi& E) {
;     ...
;         const bool has_next = S.next(ui + 1, nxt);
;         const char* nA = has_next ? (const char*)g.A + (size_t)nxt.pm * tstepA : cA; const char* nB = has_next ? (const char*)g.Bt + (size_t)nxt.pn * tstepB : cB;
;         for (int t = 0; t < nt; t += 2) {
;             const bool last = (t == nt - 2);
;             const char* a2 = last ? nA : cA + (size_t)(t + 2) * kstep; const char* b2 = last ? nB : cB + (size_t)(t + 2) * kstep;
;     ...
; #pragma unroll
;         for (int a = 0; a < 2; ++a)
; #pragma unroll
;             for (int b = 0; b < 2; ++b)
; #pragma unroll
;                 for (int m = 0; m < 4; ++m)
; #pragma unroll
;                     for (int n = 0; n < 2; ++n) acc[a][b][m][n] = (f32x4){0.f, 0.f, 0.f, 0.f};
.LBB0_942:
	s_ashr_i32 s13, s12, 31
	s_lshl_b64 s[6:7], s[12:13], 19
	s_add_u32 s14, s26, s6
	s_addc_u32 s15, s27, s7
	s_and_b64 s[6:7], s[10:11], exec
	s_cselect_b32 s13, s15, s43
	s_cselect_b32 s66, s14, s42
	s_ashr_i32 s5, s4, 31
	s_lshl_b64 s[6:7], s[4:5], 19
	s_add_u32 s16, s29, s6
	s_addc_u32 s17, s37, s7
	s_and_b64 s[6:7], s[10:11], exec
	s_cselect_b32 s5, s17, s39
	s_cselect_b32 s67, s16, s38
	s_add_u32 s6, s38, 0x40080
	s_addc_u32 s7, s39, 0
	s_add_u32 s84, s42, 0x100
	s_addc_u32 s85, s43, 0
	s_add_u32 s86, s38, 0x100
	v_mov_b32_e32 v0, 0
	s_addc_u32 s87, s39, 0
	s_mov_b32 s68, -2
	s_waitcnt lgkmcnt(0)
	v_mov_b32_e32 v1, v0
	v_mov_b64_e32 v[2:3], 0
	v_mov_b64_e32 v[4:5], 0
	v_mov_b64_e32 v[6:7], 0
	v_mov_b64_e32 v[16:17], 0
	v_mov_b64_e32 v[18:19], 0
	v_mov_b64_e32 v[20:21], 0
	v_mov_b64_e32 v[22:23], 0
	v_mov_b64_e32 v[32:33], 0
	v_mov_b64_e32 v[34:35], 0
	v_mov_b64_e32 v[36:37], 0
	v_mov_b64_e32 v[38:39], 0
	v_mov_b64_e32 v[48:49], 0
	v_mov_b64_e32 v[50:51], 0
	v_mov_b64_e32 v[52:53], 0
	v_mov_b64_e32 v[54:55], 0
	v_mov_b64_e32 v[8:9], 0
	v_mov_b64_e32 v[10:11], 0
	v_mov_b64_e32 v[12:13], 0
	v_mov_b64_e32 v[14:15], 0
	v_mov_b64_e32 v[24:25], 0
	v_mov_b64_e32 v[26:27], 0
	v_mov_b64_e32 v[28:29], 0
	v_mov_b64_e32 v[30:31], 0
	v_mov_b64_e32 v[40:41], 0
	v_mov_b64_e32 v[42:43], 0
	v_mov_b64_e32 v[44:45], 0
	v_mov_b64_e32 v[46:47], 0
	v_mov_b64_e32 v[56:57], 0
	v_mov_b64_e32 v[58:59], 0
	v_mov_b64_e32 v[60:61], 0
	v_mov_b64_e32 v[62:63], 0
	v_mov_b64_e32 v[64:65], 0
	v_mov_b64_e32 v[66:67], 0
	v_mov_b64_e32 v[68:69], 0
	v_mov_b64_e32 v[70:71], 0
	v_mov_b64_e32 v[80:81], 0
	v_mov_b64_e32 v[82:83], 0
	v_mov_b64_e32 v[84:85], 0
	v_mov_b64_e32 v[86:87], 0
	v_mov_b64_e32 v[96:97], 0
	v_mov_b64_e32 v[98:99], 0
	v_mov_b64_e32 v[100:101], 0
	v_mov_b64_e32 v[102:103], 0
	v_mov_b64_e32 v[112:113], 0
	v_mov_b64_e32 v[114:115], 0
	v_mov_b64_e32 v[116:117], 0
	v_mov_b64_e32 v[118:119], 0
	v_mov_b64_e32 v[72:73], 0
	v_mov_b64_e32 v[74:75], 0
	v_mov_b64_e32 v[76:77], 0
	v_mov_b64_e32 v[78:79], 0
	v_mov_b64_e32 v[88:89], 0
	v_mov_b64_e32 v[90:91], 0
	v_mov_b64_e32 v[92:93], 0
	v_mov_b64_e32 v[94:95], 0
	v_mov_b64_e32 v[104:105], 0
	v_mov_b64_e32 v[106:107], 0
	v_mov_b64_e32 v[108:109], 0
	v_mov_b64_e32 v[110:111], 0
	v_mov_b64_e32 v[120:121], 0
	v_mov_b64_e32 v[122:123], 0
	v_mov_b64_e32 v[124:125], 0
	v_mov_b64_e32 v[126:127], 0

; template <class Epi>
; __device__ __forceinline__ void gemm_phase(LAS unsigned char* lds, const Gemm g, const StaticOrder& S, const Epi& E) {
;     ...
;         const bool has_next = S.next(ui + 1, nxt);
;         const char* nA = has_next ? (const char*)g.A + (size_t)nxt.pm * tstepA : cA; const char* nB = has_next ? (const char*)g.Bt + (size_t)nxt.pn * tstepB : cB;
;         for (int t = 0; t < nt; t += 2) {
;             const bool last = (t == nt - 2);
;             const char* a2 = last ? nA : cA + (size_t)(t + 2) * kstep; const char* b2 = last ? nB : cB + (size_t)(t + 2) * kstep;
;     ...
; #pragma unroll
;         for (int a = 0; a < 2; ++a)
; #pragma unroll
;             for (int b = 0; b < 2; ++b)
; #pragma unroll
;                 for (int m = 0; m < 4; ++m)
; #pragma unroll
;                     for (int n = 0; n < 2; ++n) acc[a][b][m][n] = (f32x4){0.f, 0.f, 0.f, 0.f};
.LBB0_1026:
	s_ashr_i32 s7, s6, 31
	s_lshl_b64 s[14:15], s[6:7], 19
	s_add_u32 s80, s22, s14
	s_addc_u32 s81, s23, s15
	s_and_b64 s[14:15], s[8:9], exec
	s_cselect_b32 s7, s81, s13
	s_cselect_b32 s97, s80, s12
	s_ashr_i32 s39, s38, 31
	s_lshl_b64 s[14:15], s[38:39], 19
	s_add_u32 s82, s28, s14
	s_addc_u32 s83, s29, s15
	s_and_b64 s[14:15], s[8:9], exec
	s_cselect_b32 s39, s83, s11
	s_cselect_b32 vcc_lo, s82, s10
	s_add_u32 vcc_hi, s12, 0x100
	v_mov_b32_e32 v0, 0
	s_addc_u32 s68, s13, 0
	s_mov_b32 s69, -2
	v_mov_b32_e32 v1, v0
	v_mov_b64_e32 v[2:3], 0
	v_mov_b64_e32 v[60:61], 0
	v_mov_b64_e32 v[62:63], 0
	v_mov_b64_e32 v[8:9], 0
	v_mov_b64_e32 v[10:11], 0
	v_mov_b64_e32 v[104:105], 0
	v_mov_b64_e32 v[106:107], 0
	v_mov_b64_e32 v[12:13], 0
	v_mov_b64_e32 v[14:15], 0
	v_mov_b64_e32 v[108:109], 0
	v_mov_b64_e32 v[110:111], 0
	v_mov_b64_e32 v[20:21], 0
	v_mov_b64_e32 v[22:23], 0
	v_mov_b64_e32 v[116:117], 0
	v_mov_b64_e32 v[118:119], 0
	v_mov_b64_e32 v[4:5], 0
	v_mov_b64_e32 v[6:7], 0
	v_mov_b64_e32 v[64:65], 0
	v_mov_b64_e32 v[66:67], 0
	v_mov_b64_e32 v[16:17], 0
	v_mov_b64_e32 v[18:19], 0
	v_mov_b64_e32 v[112:113], 0
	v_mov_b64_e32 v[114:115], 0
	v_mov_b64_e32 v[24:25], 0
	v_mov_b64_e32 v[26:27], 0
	v_mov_b64_e32 v[120:121], 0
	v_mov_b64_e32 v[122:123], 0
	v_mov_b64_e32 v[28:29], 0
	v_mov_b64_e32 v[30:31], 0
	v_mov_b64_e32 v[124:125], 0
	v_mov_b64_e32 v[126:127], 0
	v_mov_b64_e32 v[32:33], 0
	v_mov_b64_e32 v[34:35], 0
	v_mov_b64_e32 v[128:129], 0
	v_mov_b64_e32 v[130:131], 0
	v_mov_b64_e32 v[36:37], 0
	v_mov_b64_e32 v[38:39], 0
	v_mov_b64_e32 v[132:133], 0
	v_mov_b64_e32 v[134:135], 0
	v_mov_b64_e32 v[44:45], 0
	v_mov_b64_e32 v[46:47], 0
	v_mov_b64_e32 v[140:141], 0
	v_mov_b64_e32 v[142:143], 0
	v_mov_b64_e32 v[56:57], 0
	v_mov_b64_e32 v[58:59], 0
	v_mov_b64_e32 v[72:73], 0
	v_mov_b64_e32 v[74:75], 0
	v_mov_b64_e32 v[40:41], 0
	v_mov_b64_e32 v[42:43], 0
	v_mov_b64_e32 v[136:137], 0
	v_mov_b64_e32 v[138:139], 0
	v_mov_b64_e32 v[48:49], 0
	v_mov_b64_e32 v[50:51], 0
	v_mov_b64_e32 v[144:145], 0
	v_mov_b64_e32 v[146:147], 0
	v_mov_b64_e32 v[52:53], 0
	v_mov_b64_e32 v[54:55], 0
	v_mov_b64_e32 v[148:149], 0
	v_mov_b64_e32 v[150:151], 0
	v_mov_b64_e32 v[76:77], 0
	v_mov_b64_e32 v[78:79], 0
	v_mov_b64_e32 v[80:81], 0
	v_mov_b64_e32 v[82:83], 0

; template <class Epi>
; __device__ __forceinline__ void gemm_phase(LAS unsigned char* lds, const Gemm g, const StaticOrder& S, const Epi& E) {
;     ...
;         const bool has_next = S.next(ui + 1, nxt);
;         const char* nA = has_next ? (const char*)g.A + (size_t)nxt.pm * tstepA : cA; const char* nB = has_next ? (const char*)g.Bt + (size_t)nxt.pn * tstepB : cB;
;         for (int t = 0; t < nt; t += 2) {
;             const bool last = (t == nt - 2);
;             const char* a2 = last ? nA : cA + (size_t)(t + 2) * kstep; const char* b2 = last ? nB : cB + (size_t)(t + 2) * kstep;
;             const char* a3 = a2 + kstep; const char* b3 = b2 + kstep;
;             const char* b1 = cB + (size_t)(t + 1) * kstep;
;     ...
; #pragma unroll
;         for (int a = 0; a < 2; ++a)
; #pragma unroll
;             for (int b = 0; b < 2; ++b)
; #pragma unroll
;                 for (int m = 0; m < 4; ++m)
; #pragma unroll
;                     for (int n = 0; n < 2; ++n) acc[a][b][m][n] = (f32x4){0.f, 0.f, 0.f, 0.f};
.LBB0_1139:
	s_add_u32 s12, s14, 0xb0080
	s_addc_u32 s13, s15, 0
	s_add_u32 s80, s16, 0x100
	s_addc_u32 s81, s17, 0
	s_add_u32 s82, s14, 0x100
	v_mov_b32_e32 v0, 0
	s_addc_u32 s83, s15, 0
	s_mov_b32 s68, -2
	s_waitcnt lgkmcnt(0)
	v_mov_b32_e32 v1, v0
	v_mov_b64_e32 v[2:3], 0
	v_mov_b64_e32 v[4:5], 0
	v_mov_b64_e32 v[6:7], 0
	v_mov_b64_e32 v[16:17], 0
	v_mov_b64_e32 v[18:19], 0
	v_mov_b64_e32 v[20:21], 0
	v_mov_b64_e32 v[22:23], 0
	v_mov_b64_e32 v[32:33], 0
	v_mov_b64_e32 v[34:35], 0
	v_mov_b64_e32 v[36:37], 0
	v_mov_b64_e32 v[38:39], 0
	v_mov_b64_e32 v[48:49], 0
	v_mov_b64_e32 v[50:51], 0
	v_mov_b64_e32 v[52:53], 0
	v_mov_b64_e32 v[54:55], 0
	v_mov_b64_e32 v[8:9], 0
	v_mov_b64_e32 v[10:11], 0
	v_mov_b64_e32 v[12:13], 0
	v_mov_b64_e32 v[14:15], 0
	v_mov_b64_e32 v[24:25], 0
	v_mov_b64_e32 v[26:27], 0
	v_mov_b64_e32 v[28:29], 0
	v_mov_b64_e32 v[30:31], 0
	v_mov_b64_e32 v[40:41], 0
	v_mov_b64_e32 v[42:43], 0
	v_mov_b64_e32 v[44:45], 0
	v_mov_b64_e32 v[46:47], 0
	v_mov_b64_e32 v[56:57], 0
	v_mov_b64_e32 v[58:59], 0
	v_mov_b64_e32 v[60:61], 0
	v_mov_b64_e32 v[62:63], 0
	v_mov_b64_e32 v[64:65], 0
	v_mov_b64_e32 v[66:67], 0
	v_mov_b64_e32 v[68:69], 0
	v_mov_b64_e32 v[70:71], 0
	v_mov_b64_e32 v[80:81], 0
	v_mov_b64_e32 v[82:83], 0
	v_mov_b64_e32 v[84:85], 0
	v_mov_b64_e32 v[86:87], 0
	v_mov_b64_e32 v[96:97], 0
	v_mov_b64_e32 v[98:99], 0
	v_mov_b64_e32 v[100:101], 0
	v_mov_b64_e32 v[102:103], 0
	v_mov_b64_e32 v[112:113], 0
	v_mov_b64_e32 v[114:115], 0
	v_mov_b64_e32 v[116:117], 0
	v_mov_b64_e32 v[118:119], 0
	v_mov_b64_e32 v[72:73], 0
	v_mov_b64_e32 v[74:75], 0
	v_mov_b64_e32 v[76:77], 0
	v_mov_b64_e32 v[78:79], 0
	v_mov_b64_e32 v[88:89], 0
	v_mov_b64_e32 v[90:91], 0
	v_mov_b64_e32 v[92:93], 0
	v_mov_b64_e32 v[94:95], 0
	v_mov_b64_e32 v[104:105], 0
	v_mov_b64_e32 v[106:107], 0
	v_mov_b64_e32 v[108:109], 0
	v_mov_b64_e32 v[110:111], 0
	v_mov_b64_e32 v[120:121], 0
	v_mov_b64_e32 v[122:123], 0
	v_mov_b64_e32 v[124:125], 0
	v_mov_b64_e32 v[126:127], 0
